# chain wave: the first two re-polls of the per-slot LDS ready flag no longer sleep (shorter hand-off detection latency when the chain is starved)
# speedup vs baseline: 1.0041x; 1.0041x over previous
; __device__ void phase_rwkv_dist(const Params& p, LAS unsigned char* lds, int wg, int nwg) {
;     ...
;                 { unsigned sp = 0; while (!dead && lflag[ci % RD_NL] != (unsigned)(ci + 1)) { __builtin_amdgcn_s_sleep(1); if (++sp > RD_SPIN_MAX) { if (lane == 0) atomicAdd(ERR, 1u); dead = true; } } }
;                 asm volatile("" ::: "memory");
.LBB0_782:
	v_mov_b32_e32 v0, s17
	ds_read_b32 v0, v0
	s_waitcnt lgkmcnt(0)
	v_cmp_eq_u32_e32 vcc, s7, v0
	s_cbranch_vccnz .LBB0_781
	v_mov_b32_e32 v0, s17
	s_nop 0
	ds_read_b32 v0, v0
	s_waitcnt lgkmcnt(0)
	v_cmp_ne_u32_e32 vcc, s7, v0
	s_cbranch_vccz .LBB0_781
	v_mov_b32_e32 v0, s17
	s_nop 0
	ds_read_b32 v0, v0
	s_waitcnt lgkmcnt(0)
	v_cmp_ne_u32_e32 vcc, s7, v0
	s_cbranch_vccz .LBB0_781
	s_cmp_gt_u32 s18, 0x7fffd
	s_cselect_b64 s[0:1], -1, 0
	s_and_b64 s[2:3], s[4:5], s[0:1]
	s_sleep 1
	s_and_saveexec_b64 s[0:1], s[2:3]
	s_cbranch_execz .LBB0_788
	s_mov_b64 s[2:3], exec
	v_mbcnt_lo_u32_b32 v0, s2, 0
	v_mbcnt_hi_u32_b32 v0, s3, v0
	v_cmp_eq_u32_e32 vcc, 0, v0
	s_and_b64 s[38:39], exec, vcc
	s_mov_b64 exec, s[38:39]
	s_cbranch_execz .LBB0_788
	s_bcnt1_i32_b64 s2, s[2:3]
	v_mov_b32_e32 v0, s2
	global_atomic_add v1, v0, s[96:97]
